# up-proj epilogue: wave halves re-aligned around the halo exchange (one barrier, halves compute concurrently) + attention static prio for waves 4-7 + scalar mul/add pairs packed
# speedup vs baseline: 1.0758x; 1.0166x over previous
.LBB0_701:
	s_or_b64 exec, exec, s[20:21]
	v_readlane_b32 s0, v254, 24
	s_cmpk_lt_u32 s0, 0x100
	s_cbranch_scc1 .Lup_e1_skip
	s_barrier
.Lup_e1_skip:
	s_and_b64 vcc, exec, s[46:47]
	s_mov_b32 s48, s94
	s_mov_b32 s52, s92
	s_mov_b64 s[34:35], s[14:15]
	s_mov_b64 s[20:21], s[78:79]
	s_cbranch_vccnz .LBB0_751

.LBB0_705:
	v_add_u32_e32 v86, s61, v184
	ds_read_b128 v[74:77], v86
	ds_read_b128 v[78:81], v86 offset:1024
	ds_read_b128 v[82:85], v86 offset:2048
	ds_read_b128 v[86:89], v86 offset:3072
	s_add_u32 s0, s20, 0xfffc0080
	s_addc_u32 s1, s21, -1
	s_cmp_eq_u32 vcc_lo, 12
	s_cselect_b32 s51, s49, s1
	s_cselect_b32 s50, s53, s0
	s_cselect_b32 s35, s54, s95
	s_cselect_b32 s34, s55, s93
	v_lshl_add_u64 v[180:181], s[20:21], 0, v[172:173]
	s_add_i32 m0, s85, 0xc000
	ds_read_b128 v[146:149], v201
	ds_read_b128 v[150:153], v201 offset:1024
	ds_read_b128 v[154:157], v201 offset:2048
	ds_read_b128 v[158:161], v201 offset:3072
	ds_read_b128 v[162:165], v201 offset:4096
	ds_read_b128 v[166:169], v201 offset:5120
	ds_read_b128 v[176:179], v201 offset:6144
	ds_read_b128 v[194:197], v201 offset:7168
	global_load_lds_dwordx4 v[180:181], off
	v_lshl_add_u64 v[180:181], s[20:21], 0, v[174:175]
	s_add_i32 m0, s85, 0xe000
	s_nop 0
	global_load_lds_dwordx4 v[180:181], off
	s_waitcnt lgkmcnt(8)
	s_barrier
	s_waitcnt lgkmcnt(0)
	s_setprio 1
	s_waitcnt lgkmcnt(0)
	v_mfma_f32_16x16x32_bf16 v[126:129], v[74:77], v[146:149], v[126:129]
	v_mfma_f32_16x16x32_bf16 v[46:49], v[82:85], v[146:149], v[46:49]
	v_mfma_f32_16x16x32_bf16 v[138:141], v[74:77], v[154:157], v[138:141]
	v_mfma_f32_16x16x32_bf16 v[58:61], v[82:85], v[154:157], v[58:61]
	v_mfma_f32_16x16x32_bf16 v[130:133], v[74:77], v[162:165], v[130:133]
	v_mfma_f32_16x16x32_bf16 v[50:53], v[82:85], v[162:165], v[50:53]
	v_mfma_f32_16x16x32_bf16 v[114:117], v[74:77], v[176:179], v[114:117]
	v_mfma_f32_16x16x32_bf16 v[34:37], v[82:85], v[176:179], v[34:37]
	v_mfma_f32_16x16x32_bf16 v[126:129], v[78:81], v[150:153], v[126:129]
	v_mfma_f32_16x16x32_bf16 v[46:49], v[86:89], v[150:153], v[46:49]
	v_mfma_f32_16x16x32_bf16 v[138:141], v[78:81], v[158:161], v[138:141]
	v_mfma_f32_16x16x32_bf16 v[58:61], v[86:89], v[158:161], v[58:61]
	v_mfma_f32_16x16x32_bf16 v[130:133], v[78:81], v[166:169], v[130:133]
	v_mfma_f32_16x16x32_bf16 v[50:53], v[86:89], v[166:169], v[50:53]
	v_mfma_f32_16x16x32_bf16 v[114:117], v[78:81], v[194:197], v[114:117]
	v_mfma_f32_16x16x32_bf16 v[34:37], v[86:89], v[194:197], v[34:37]
	s_setprio 0
	s_barrier
	v_add_u32_e32 v180, s19, v184
	s_mov_b32 m0, s62
	ds_read_b128 v[204:207], v180
	ds_read_b128 v[208:211], v180 offset:1024
	ds_read_b128 v[212:215], v180 offset:2048
	ds_read_b128 v[216:219], v180 offset:3072
	v_lshl_add_u64 v[180:181], s[34:35], 0, v[0:1]
	global_load_lds_dwordx4 v[180:181], off
	v_lshl_add_u64 v[220:221], s[34:35], 0, v[170:171]
	s_mov_b32 m0, s63
	s_nop 0
	global_load_lds_dwordx4 v[220:221], off
	s_barrier
	s_waitcnt lgkmcnt(0)
	s_setprio 1
	s_waitcnt lgkmcnt(0)
	v_mfma_f32_16x16x32_bf16 v[142:145], v[204:207], v[146:149], v[142:145]
	v_mfma_f32_16x16x32_bf16 v[62:65], v[212:215], v[146:149], v[62:65]
	v_mfma_f32_16x16x32_bf16 v[134:137], v[204:207], v[154:157], v[134:137]
	v_mfma_f32_16x16x32_bf16 v[54:57], v[212:215], v[154:157], v[54:57]
	v_mfma_f32_16x16x32_bf16 v[122:125], v[204:207], v[162:165], v[122:125]
	v_mfma_f32_16x16x32_bf16 v[42:45], v[212:215], v[162:165], v[42:45]
	v_mfma_f32_16x16x32_bf16 v[118:121], v[204:207], v[176:179], v[118:121]
	v_mfma_f32_16x16x32_bf16 v[38:41], v[212:215], v[176:179], v[38:41]
	v_mfma_f32_16x16x32_bf16 v[142:145], v[208:211], v[150:153], v[142:145]
	v_mfma_f32_16x16x32_bf16 v[62:65], v[216:219], v[150:153], v[62:65]
	v_mfma_f32_16x16x32_bf16 v[134:137], v[208:211], v[158:161], v[134:137]
	v_mfma_f32_16x16x32_bf16 v[54:57], v[216:219], v[158:161], v[54:57]
	v_mfma_f32_16x16x32_bf16 v[122:125], v[208:211], v[166:169], v[122:125]
	v_mfma_f32_16x16x32_bf16 v[42:45], v[216:219], v[166:169], v[42:45]
	v_mfma_f32_16x16x32_bf16 v[118:121], v[208:211], v[194:197], v[118:121]
	v_mfma_f32_16x16x32_bf16 v[38:41], v[216:219], v[194:197], v[38:41]
	s_setprio 0
	s_mov_b32 m0, s85
	v_lshl_add_u64 v[222:223], s[50:51], 0, v[0:1]
	s_barrier
	ds_read_b128 v[146:149], v201 offset:16384
	ds_read_b128 v[150:153], v201 offset:17408
	ds_read_b128 v[154:157], v201 offset:18432
	ds_read_b128 v[158:161], v201 offset:19456
	ds_read_b128 v[162:165], v201 offset:20480
	ds_read_b128 v[166:169], v201 offset:21504
	ds_read_b128 v[176:179], v201 offset:22528
	ds_read_b128 v[194:197], v201 offset:23552
	global_load_lds_dwordx4 v[222:223], off
	v_lshl_add_u64 v[232:233], s[50:51], 0, v[170:171]
	s_mov_b32 m0, s86
	s_nop 0
	global_load_lds_dwordx4 v[232:233], off
	s_barrier
	s_waitcnt lgkmcnt(0)
	s_setprio 1
	s_waitcnt lgkmcnt(0)
	v_mfma_f32_16x16x32_bf16 v[106:109], v[74:77], v[146:149], v[106:109]
	v_mfma_f32_16x16x32_bf16 v[30:33], v[82:85], v[146:149], v[30:33]
	v_mfma_f32_16x16x32_bf16 v[102:105], v[74:77], v[154:157], v[102:105]
	v_mfma_f32_16x16x32_bf16 v[22:25], v[82:85], v[154:157], v[22:25]
	v_mfma_f32_16x16x32_bf16 v[94:97], v[74:77], v[162:165], v[94:97]
	v_mfma_f32_16x16x32_bf16 v[14:17], v[82:85], v[162:165], v[14:17]
	v_mfma_f32_16x16x32_bf16 v[66:69], v[74:77], v[176:179], v[66:69]
	v_mfma_f32_16x16x32_bf16 v[2:5], v[82:85], v[176:179], v[2:5]
	v_mfma_f32_16x16x32_bf16 v[106:109], v[78:81], v[150:153], v[106:109]
	v_mfma_f32_16x16x32_bf16 v[30:33], v[86:89], v[150:153], v[30:33]
	v_mfma_f32_16x16x32_bf16 v[102:105], v[78:81], v[158:161], v[102:105]
	v_mfma_f32_16x16x32_bf16 v[22:25], v[86:89], v[158:161], v[22:25]
	v_mfma_f32_16x16x32_bf16 v[94:97], v[78:81], v[166:169], v[94:97]
	v_mfma_f32_16x16x32_bf16 v[14:17], v[86:89], v[166:169], v[14:17]
	v_mfma_f32_16x16x32_bf16 v[66:69], v[78:81], v[194:197], v[66:69]
	v_mfma_f32_16x16x32_bf16 v[2:5], v[86:89], v[194:197], v[2:5]
	s_setprio 0
	s_barrier
	s_add_u32 s0, s34, 0x40000
	s_addc_u32 s1, s35, 0
	s_mov_b32 m0, s90
	v_lshl_add_u64 v[74:75], s[0:1], 0, v[0:1]
	global_load_lds_dwordx4 v[74:75], off
	v_lshl_add_u64 v[74:75], s[0:1], 0, v[170:171]
	s_mov_b32 m0, s26
	s_nop 0
	global_load_lds_dwordx4 v[74:75], off
	s_waitcnt vmcnt(6)
	s_barrier
	s_setprio 1
	v_mfma_f32_16x16x32_bf16 v[26:29], v[212:215], v[146:149], v[26:29]
	v_mfma_f32_16x16x32_bf16 v[18:21], v[212:215], v[154:157], v[18:21]
	v_mfma_f32_16x16x32_bf16 v[10:13], v[212:215], v[162:165], v[10:13]
	v_mfma_f32_16x16x32_bf16 v[70:73], v[204:207], v[176:179], v[70:73]
	v_mfma_f32_16x16x32_bf16 v[6:9], v[212:215], v[176:179], v[6:9]
	v_mfma_f32_16x16x32_bf16 v[74:77], v[204:207], v[146:149], v[110:113]
	v_mfma_f32_16x16x32_bf16 v[26:29], v[216:219], v[150:153], v[26:29]
	v_mfma_f32_16x16x32_bf16 v[78:81], v[204:207], v[154:157], v[98:101]
	v_mfma_f32_16x16x32_bf16 v[18:21], v[216:219], v[158:161], v[18:21]
	v_mfma_f32_16x16x32_bf16 v[82:85], v[204:207], v[162:165], v[90:93]
	v_mfma_f32_16x16x32_bf16 v[10:13], v[216:219], v[166:169], v[10:13]
	v_mfma_f32_16x16x32_bf16 v[70:73], v[208:211], v[194:197], v[70:73]
	v_mfma_f32_16x16x32_bf16 v[6:9], v[216:219], v[194:197], v[6:9]
	v_mfma_f32_16x16x32_bf16 v[74:77], v[208:211], v[150:153], v[74:77]
	v_mfma_f32_16x16x32_bf16 v[78:81], v[208:211], v[158:161], v[78:81]
	v_mfma_f32_16x16x32_bf16 v[82:85], v[208:211], v[166:169], v[82:85]
	s_setprio 0
	v_add_u32_e32 v110, s36, v184
	s_barrier
	ds_read_b128 v[86:89], v110
	ds_read_b128 v[90:93], v110 offset:1024
	ds_read_b128 v[98:101], v110 offset:2048
	ds_read_b128 v[110:113], v110 offset:3072
	s_add_u32 s0, s50, 0x40000
	s_addc_u32 s1, s51, 0
	s_mov_b32 m0, s28
	v_lshl_add_u64 v[204:205], s[0:1], 0, v[0:1]
	ds_read_b128 v[146:149], v201 offset:32768
	ds_read_b128 v[150:153], v201 offset:33792
	ds_read_b128 v[154:157], v201 offset:34816
	ds_read_b128 v[158:161], v201 offset:35840
	ds_read_b128 v[162:165], v201 offset:36864
	ds_read_b128 v[166:169], v201 offset:37888
	ds_read_b128 v[176:179], v201 offset:38912
	ds_read_b128 v[194:197], v201 offset:39936
	global_load_lds_dwordx4 v[204:205], off
	v_lshl_add_u64 v[204:205], s[0:1], 0, v[170:171]
	s_mov_b32 m0, s30
	s_nop 0
	global_load_lds_dwordx4 v[204:205], off
	s_waitcnt lgkmcnt(8)
	s_barrier
	s_waitcnt lgkmcnt(0)
	s_setprio 1
	s_waitcnt lgkmcnt(0)
	v_mfma_f32_16x16x32_bf16 v[126:129], v[86:89], v[146:149], v[126:129]
	v_mfma_f32_16x16x32_bf16 v[46:49], v[98:101], v[146:149], v[46:49]
	v_mfma_f32_16x16x32_bf16 v[138:141], v[86:89], v[154:157], v[138:141]
	v_mfma_f32_16x16x32_bf16 v[58:61], v[98:101], v[154:157], v[58:61]
	v_mfma_f32_16x16x32_bf16 v[130:133], v[86:89], v[162:165], v[130:133]
	v_mfma_f32_16x16x32_bf16 v[50:53], v[98:101], v[162:165], v[50:53]
	v_mfma_f32_16x16x32_bf16 v[114:117], v[86:89], v[176:179], v[114:117]
	v_mfma_f32_16x16x32_bf16 v[34:37], v[98:101], v[176:179], v[34:37]
	v_mfma_f32_16x16x32_bf16 v[126:129], v[90:93], v[150:153], v[126:129]
	v_mfma_f32_16x16x32_bf16 v[46:49], v[110:113], v[150:153], v[46:49]
	v_mfma_f32_16x16x32_bf16 v[138:141], v[90:93], v[158:161], v[138:141]
	v_mfma_f32_16x16x32_bf16 v[58:61], v[110:113], v[158:161], v[58:61]
	v_mfma_f32_16x16x32_bf16 v[130:133], v[90:93], v[166:169], v[130:133]
	v_mfma_f32_16x16x32_bf16 v[50:53], v[110:113], v[166:169], v[50:53]
	v_mfma_f32_16x16x32_bf16 v[114:117], v[90:93], v[194:197], v[114:117]
	v_mfma_f32_16x16x32_bf16 v[34:37], v[110:113], v[194:197], v[34:37]
	s_setprio 0
	s_barrier
	s_mov_b32 m0, s58
	v_add_u32_e32 v216, s8, v184
	v_lshl_add_u64 v[180:181], v[180:181], 0, s[88:89]
	ds_read_b128 v[204:207], v216
	ds_read_b128 v[208:211], v216 offset:1024
	ds_read_b128 v[212:215], v216 offset:2048
	ds_read_b128 v[216:219], v216 offset:3072
	global_load_lds_dwordx4 v[180:181], off
	v_lshl_add_u64 v[180:181], v[220:221], 0, s[88:89]
	s_mov_b32 m0, s38
	s_nop 0
	global_load_lds_dwordx4 v[180:181], off
	s_barrier
	s_waitcnt lgkmcnt(0)
	s_setprio 1
	s_waitcnt lgkmcnt(0)
	v_mfma_f32_16x16x32_bf16 v[142:145], v[204:207], v[146:149], v[142:145]
	v_mfma_f32_16x16x32_bf16 v[62:65], v[212:215], v[146:149], v[62:65]
	v_mfma_f32_16x16x32_bf16 v[134:137], v[204:207], v[154:157], v[134:137]
	v_mfma_f32_16x16x32_bf16 v[54:57], v[212:215], v[154:157], v[54:57]
	v_mfma_f32_16x16x32_bf16 v[122:125], v[204:207], v[162:165], v[122:125]
	v_mfma_f32_16x16x32_bf16 v[42:45], v[212:215], v[162:165], v[42:45]
	v_mfma_f32_16x16x32_bf16 v[118:121], v[204:207], v[176:179], v[118:121]
	v_mfma_f32_16x16x32_bf16 v[38:41], v[212:215], v[176:179], v[38:41]
	v_mfma_f32_16x16x32_bf16 v[142:145], v[208:211], v[150:153], v[142:145]
	v_mfma_f32_16x16x32_bf16 v[62:65], v[216:219], v[150:153], v[62:65]
	v_mfma_f32_16x16x32_bf16 v[134:137], v[208:211], v[158:161], v[134:137]
	v_mfma_f32_16x16x32_bf16 v[54:57], v[216:219], v[158:161], v[54:57]
	v_mfma_f32_16x16x32_bf16 v[122:125], v[208:211], v[166:169], v[122:125]
	v_mfma_f32_16x16x32_bf16 v[42:45], v[216:219], v[166:169], v[42:45]
	v_mfma_f32_16x16x32_bf16 v[118:121], v[208:211], v[194:197], v[118:121]
	v_mfma_f32_16x16x32_bf16 v[38:41], v[216:219], v[194:197], v[38:41]
	s_setprio 0
	s_mov_b32 m0, s96
	v_lshl_add_u64 v[180:181], v[222:223], 0, s[88:89]
	s_barrier
	ds_read_b128 v[146:149], v201 offset:49152
	ds_read_b128 v[150:153], v201 offset:50176
	ds_read_b128 v[154:157], v201 offset:51200
	ds_read_b128 v[158:161], v201 offset:52224
	ds_read_b128 v[162:165], v201 offset:53248
	ds_read_b128 v[166:169], v201 offset:54272
	ds_read_b128 v[176:179], v201 offset:55296
	ds_read_b128 v[194:197], v201 offset:56320
	global_load_lds_dwordx4 v[180:181], off
	v_lshl_add_u64 v[180:181], v[232:233], 0, s[88:89]
	s_mov_b32 m0, s4
	s_nop 0
	global_load_lds_dwordx4 v[180:181], off
	s_barrier
	s_waitcnt lgkmcnt(0)
	s_setprio 1
	s_waitcnt lgkmcnt(0)
	v_mfma_f32_16x16x32_bf16 v[106:109], v[86:89], v[146:149], v[106:109]
	v_mfma_f32_16x16x32_bf16 v[30:33], v[98:101], v[146:149], v[30:33]
	v_mfma_f32_16x16x32_bf16 v[102:105], v[86:89], v[154:157], v[102:105]
	v_mfma_f32_16x16x32_bf16 v[22:25], v[98:101], v[154:157], v[22:25]
	v_mfma_f32_16x16x32_bf16 v[94:97], v[86:89], v[162:165], v[94:97]
	v_mfma_f32_16x16x32_bf16 v[14:17], v[98:101], v[162:165], v[14:17]
	v_mfma_f32_16x16x32_bf16 v[66:69], v[86:89], v[176:179], v[66:69]
	v_mfma_f32_16x16x32_bf16 v[2:5], v[98:101], v[176:179], v[2:5]
	v_mfma_f32_16x16x32_bf16 v[106:109], v[90:93], v[150:153], v[106:109]
	v_mfma_f32_16x16x32_bf16 v[30:33], v[110:113], v[150:153], v[30:33]
	v_mfma_f32_16x16x32_bf16 v[102:105], v[90:93], v[158:161], v[102:105]
	v_mfma_f32_16x16x32_bf16 v[22:25], v[110:113], v[158:161], v[22:25]
	v_mfma_f32_16x16x32_bf16 v[94:97], v[90:93], v[166:169], v[94:97]
	v_mfma_f32_16x16x32_bf16 v[14:17], v[110:113], v[166:169], v[14:17]
	v_mfma_f32_16x16x32_bf16 v[66:69], v[90:93], v[194:197], v[66:69]
	v_mfma_f32_16x16x32_bf16 v[2:5], v[110:113], v[194:197], v[2:5]
	s_setprio 0
	s_barrier
	s_add_u32 s0, s34, 0x40080
	s_addc_u32 s1, s35, 0
	s_mov_b32 m0, s10
	v_lshl_add_u64 v[86:87], s[0:1], 0, v[0:1]
	global_load_lds_dwordx4 v[86:87], off
	v_lshl_add_u64 v[86:87], s[0:1], 0, v[170:171]
	s_mov_b32 m0, s11
	s_nop 0
	global_load_lds_dwordx4 v[86:87], off
	s_waitcnt vmcnt(6)
	s_barrier
	s_setprio 1
	v_mfma_f32_16x16x32_bf16 v[74:77], v[204:207], v[146:149], v[74:77]
	v_mfma_f32_16x16x32_bf16 v[110:113], v[208:211], v[150:153], v[74:77]
	v_mfma_f32_16x16x32_bf16 v[74:77], v[204:207], v[154:157], v[78:81]
	v_mfma_f32_16x16x32_bf16 v[26:29], v[212:215], v[146:149], v[26:29]
	v_mfma_f32_16x16x32_bf16 v[98:101], v[208:211], v[158:161], v[74:77]
	v_mfma_f32_16x16x32_bf16 v[18:21], v[212:215], v[154:157], v[18:21]
	v_mfma_f32_16x16x32_bf16 v[74:77], v[204:207], v[162:165], v[82:85]
	v_mfma_f32_16x16x32_bf16 v[10:13], v[212:215], v[162:165], v[10:13]
	v_mfma_f32_16x16x32_bf16 v[70:73], v[204:207], v[176:179], v[70:73]
	v_mfma_f32_16x16x32_bf16 v[6:9], v[212:215], v[176:179], v[6:9]
	v_mfma_f32_16x16x32_bf16 v[26:29], v[216:219], v[150:153], v[26:29]
	v_mfma_f32_16x16x32_bf16 v[18:21], v[216:219], v[158:161], v[18:21]
	v_mfma_f32_16x16x32_bf16 v[90:93], v[208:211], v[166:169], v[74:77]
	v_mfma_f32_16x16x32_bf16 v[10:13], v[216:219], v[166:169], v[10:13]
	v_mfma_f32_16x16x32_bf16 v[70:73], v[208:211], v[194:197], v[70:73]
	v_mfma_f32_16x16x32_bf16 v[6:9], v[216:219], v[194:197], v[6:9]
	s_setprio 0
	s_add_i32 vcc_lo, vcc_lo, 2
	s_add_u32 s20, s20, 0x100
	s_addc_u32 s21, s21, 0
	s_add_u32 s93, s93, 0x100
	s_addc_u32 s95, s95, 0
	s_cmp_gt_u32 vcc_lo, 13
	s_barrier
	s_cbranch_scc0 .LBB0_705
	s_mov_b32 s100, 0xbfb8aa3b
	v_lshl_or_b32 v180, s48, 7, v185
	v_ashrrev_i32_e32 v181, 31, v180
	v_lshlrev_b64 v[74:75], 2, v[180:181]
	v_lshl_add_u64 v[76:77], s[2:3], 0, v[74:75]
	v_lshl_add_u64 v[86:87], s[76:77], 0, v[74:75]
	v_lshl_add_u64 v[88:89], s[80:81], 0, v[74:75]
	v_lshl_add_u64 v[158:159], s[16:17], 0, v[74:75]
	global_load_dwordx4 v[82:85], v[76:77], off offset:16
	global_load_dwordx4 v[154:157], v[76:77], off
	global_load_dwordx4 v[78:81], v[86:87], off offset:16
	global_load_dwordx4 v[150:153], v[86:87], off
	s_nop 0
	global_load_dwordx4 v[74:77], v[88:89], off offset:16
	global_load_dwordx4 v[146:149], v[88:89], off
	s_nop 0
	global_load_dwordx4 v[86:89], v[158:159], off offset:16
	s_nop 0
	global_load_dwordx4 v[158:161], v[158:159], off
	v_readlane_b32 s0, v254, 24
	s_cmpk_gt_u32 s0, 0xff
	s_cbranch_scc1 .Lup_e0_skip
	s_barrier
.Lup_e0_skip:
	v_cmp_lt_i32_e32 vcc, 14, v182
	s_mov_b64 s[34:35], 0
	s_and_saveexec_b64 s[0:1], vcc
	s_xor_b64 s[20:21], exec, s[0:1]
	s_mov_b64 s[34:35], exec
	s_or_saveexec_b64 s[20:21], s[20:21]
	v_mov_b64_e32 v[164:165], v[116:117]
	v_mov_b32_e32 v166, s29
	v_mov_b64_e32 v[162:163], v[114:115]
	s_xor_b64 exec, exec, s[20:21]
	s_andn2_b64 s[0:1], s[34:35], exec
	s_and_b64 s[34:35], s[40:41], exec
	v_mov_b64_e32 v[164:165], v[128:129]
	v_mov_b32_e32 v166, s65
	s_or_b64 s[34:35], s[0:1], s[34:35]
	v_mov_b64_e32 v[162:163], v[126:127]
	s_or_b64 exec, exec, s[20:21]
	s_and_saveexec_b64 s[20:21], s[34:35]
	s_cbranch_execz .LBB0_727
	v_lshl_add_u32 v166, v185, 2, v166
	ds_write_b128 v166, v[162:165]
	v_mov_b64_e32 v[164:165], v[36:37]
	v_cmp_gt_i32_e32 vcc, 15, v182
	s_mov_b64 s[48:49], -1
	v_mov_b32_e32 v166, 0x210
	v_mov_b64_e32 v[162:163], v[34:35]
	s_and_saveexec_b64 s[34:35], vcc
	s_cbranch_execz .LBB0_715
	v_cmp_eq_u32_e32 vcc, 0, v182
	s_mov_b64 s[48:49], 0
	v_mov_b32_e32 v166, 0x210
	s_and_saveexec_b64 s[50:51], vcc
	s_mov_b64 s[48:49], exec
	v_mov_b32_e32 v166, 16
	s_or_b64 exec, exec, s[50:51]
	v_mov_b64_e32 v[164:165], v[48:49]
	s_orn2_b64 s[48:49], s[48:49], exec
	v_mov_b64_e32 v[162:163], v[46:47]

.LBB0_727:
	s_or_b64 exec, exec, s[20:21]
	s_waitcnt lgkmcnt(0)
	s_barrier
	v_cndmask_b32_e64 v163, 0, 1, s[66:67]
	v_mov_b32_e32 v162, 0
	v_cmp_ne_u32_e64 s[48:49], 1, v163
	s_andn2_b64 vcc, exec, s[66:67]
	v_mov_b32_e32 v166, 0
	v_mov_b32_e32 v167, 0
	v_mov_b32_e32 v168, 0
	v_mov_b32_e32 v169, 0
	s_cbranch_vccnz .LBB0_729
	ds_read_b128 v[166:169], v188

.LBB0_731:
	ds_bpermute_b32 v242, v202, v126
	ds_bpermute_b32 v243, v202, v127
	ds_bpermute_b32 v178, v203, v126
	ds_bpermute_b32 v179, v203, v127
	ds_bpermute_b32 v244, v202, v128
	ds_bpermute_b32 v245, v202, v129
	ds_bpermute_b32 v246, v203, v138
	ds_bpermute_b32 v248, v203, v139
	ds_bpermute_b32 v194, v203, v128
	ds_bpermute_b32 v195, v203, v129
	ds_bpermute_b32 v247, v203, v140
	ds_bpermute_b32 v249, v203, v141
	s_waitcnt lgkmcnt(0)
	v_cndmask_b32_e64 v167, v243, v167, s[40:41]
	v_cndmask_b32_e64 v166, v242, v166, s[40:41]
	s_waitcnt vmcnt(0)
	v_pk_fma_f32 v[166:167], v[154:155], v[166:167], v[158:159]
	v_cndmask_b32_e64 v169, v245, v169, s[40:41]
	v_cndmask_b32_e64 v168, v244, v168, s[40:41]
	v_cndmask_b32_e64 v179, v179, v248, s[42:43]
	v_cndmask_b32_e64 v178, v178, v246, s[42:43]
	v_pk_fma_f32 v[166:167], v[126:127], v[150:151], v[166:167]
	v_pk_fma_f32 v[168:169], v[156:157], v[168:169], v[160:161]
	v_pk_fma_f32 v[166:167], v[146:147], v[178:179], v[166:167]
	v_cndmask_b32_e64 v195, v195, v249, s[42:43]
	v_cndmask_b32_e64 v194, v194, v247, s[42:43]
	v_pk_fma_f32 v[168:169], v[128:129], v[152:153], v[168:169]
	v_pk_mul_f32 v[178:179], v[166:167], s[100:101] op_sel_hi:[1,0]
	v_exp_f32_e32 v178, v178
	v_exp_f32_e32 v179, v179
	v_pk_fma_f32 v[168:169], v[148:149], v[194:195], v[168:169]
	s_mul_i32 s0, s52, 0x10800
	v_pk_mul_f32 v[194:195], v[168:169], s[100:101] op_sel_hi:[1,0]
	v_exp_f32_e32 v194, v194
	v_exp_f32_e32 v195, v195
	v_pk_add_f32 v[178:179], v[178:179], 1.0 op_sel_hi:[1,0]
	v_rcp_f32_e32 v178, v178
	v_rcp_f32_e32 v179, v179
	v_pk_add_f32 v[194:195], v[194:195], 1.0 op_sel_hi:[1,0]
	v_rcp_f32_e32 v194, v194
	v_rcp_f32_e32 v195, v195
	s_mul_hi_i32 s1, s52, 0x10800
	s_add_u32 s0, s82, s0
	ds_bpermute_b32 v213, v202, v138
	ds_bpermute_b32 v215, v202, v139
	ds_bpermute_b32 v216, v202, v140
	ds_bpermute_b32 v218, v202, v141
	ds_bpermute_b32 v205, v202, v130
	ds_bpermute_b32 v214, v203, v130
	ds_bpermute_b32 v207, v202, v131
	ds_bpermute_b32 v219, v203, v131
	ds_bpermute_b32 v206, v202, v132
	ds_bpermute_b32 v217, v203, v132
	ds_bpermute_b32 v208, v202, v133
	ds_bpermute_b32 v220, v203, v133
	ds_bpermute_b32 v209, v202, v114
	ds_bpermute_b32 v221, v203, v114
	ds_bpermute_b32 v211, v202, v115
	ds_bpermute_b32 v223, v203, v115
	ds_bpermute_b32 v210, v202, v116
	ds_bpermute_b32 v222, v203, v116
	ds_bpermute_b32 v212, v202, v117
	ds_bpermute_b32 v250, v203, v117
	v_pk_mul_f32 v[178:179], v[166:167], v[178:179]
	s_addc_u32 s1, s83, s1
	v_pk_mul_f32 v[178:179], v[142:143], v[178:179]
	v_lshl_add_u64 v[176:177], v[180:181], 2, s[0:1]
	v_lshl_add_u32 v204, s52, 8, v183
	v_pk_mul_f32 v[194:195], v[168:169], v[194:195]
	v_cvt_pk_bf16_f32 v196, v178, v179
	v_mov_b64_e32 v[178:179], s[22:23]
	s_movk_i32 s0, 0x1600
	v_pk_mul_f32 v[194:195], v[144:145], v[194:195]
	v_mad_i64_i32 v[178:179], s[0:1], v204, s0, v[178:179]
	v_cvt_pk_bf16_f32 v197, v194, v195
	v_lshl_add_u64 v[178:179], v[180:181], 1, v[178:179]
	global_store_dwordx2 v[178:179], v[196:197], off
	s_and_saveexec_b64 s[20:21], s[44:45]
	s_cbranch_execz .LBB0_733
	global_store_dwordx4 v[176:177], v[166:169], off
	s_nop 1
	v_add_co_u32_e32 v166, vcc, 0x2000, v176
	s_nop 1
	v_addc_co_u32_e32 v167, vcc, 0, v177, vcc
	global_store_dwordx4 v[166:167], v[142:145], off offset:3072
	s_nop 1
	v_add_co_u32_e32 v142, vcc, 0x5000, v176
	s_nop 1
	v_addc_co_u32_e32 v143, vcc, 0, v177, vcc
	global_store_dwordx4 v[142:143], v[126:129], off offset:2048
.LBB0_733:
	s_or_b64 exec, exec, s[20:21]
	s_waitcnt lgkmcnt(14)
	v_cndmask_b32_e64 v126, v213, v242, s[40:41]
	v_cndmask_b32_e64 v127, v215, v243, s[40:41]
	v_cndmask_b32_e64 v128, v216, v244, s[40:41]
	v_cndmask_b32_e64 v129, v218, v245, s[40:41]
	v_pk_fma_f32 v[128:129], v[156:157], v[128:129], v[160:161]
	v_pk_fma_f32 v[126:127], v[154:155], v[126:127], v[158:159]
	s_waitcnt lgkmcnt(12)
	v_cndmask_b32_e64 v143, v248, v219, s[42:43]
	v_cndmask_b32_e64 v142, v246, v214, s[42:43]
	s_waitcnt lgkmcnt(8)
	v_cndmask_b32_e64 v145, v249, v220, s[42:43]
	v_cndmask_b32_e64 v144, v247, v217, s[42:43]
	v_pk_fma_f32 v[126:127], v[138:139], v[150:151], v[126:127]
	v_pk_fma_f32 v[128:129], v[140:141], v[152:153], v[128:129]
	v_pk_fma_f32 v[126:127], v[146:147], v[142:143], v[126:127]
	v_pk_fma_f32 v[128:129], v[148:149], v[144:145], v[128:129]
	v_pk_mul_f32 v[138:139], v[126:127], s[100:101] op_sel_hi:[1,0]
	v_pk_mul_f32 v[140:141], v[128:129], s[100:101] op_sel_hi:[1,0]
	v_exp_f32_e32 v138, v138
	v_exp_f32_e32 v139, v139
	v_exp_f32_e32 v140, v140
	v_exp_f32_e32 v141, v141
	v_pk_add_f32 v[138:139], v[138:139], 1.0 op_sel_hi:[1,0]
	v_pk_add_f32 v[140:141], v[140:141], 1.0 op_sel_hi:[1,0]
	v_rcp_f32_e32 v138, v138
	v_rcp_f32_e32 v139, v139
	v_rcp_f32_e32 v140, v140
	v_rcp_f32_e32 v141, v141
	v_or_b32_e32 v142, 16, v204
	v_pk_mul_f32 v[126:127], v[126:127], v[138:139]
	s_movk_i32 s18, 0x1600
	v_pk_mul_f32 v[128:129], v[128:129], v[140:141]
	v_pk_mul_f32 v[126:127], v[134:135], v[126:127]
	v_pk_mul_f32 v[128:129], v[136:137], v[128:129]
	v_mov_b64_e32 v[136:137], s[22:23]
	v_cvt_pk_bf16_f32 v134, v126, v127
	v_cvt_pk_bf16_f32 v135, v128, v129
	v_mad_i64_i32 v[126:127], s[0:1], v142, s18, v[136:137]
	v_lshlrev_b64 v[128:129], 1, v[180:181]
	v_lshl_add_u64 v[126:127], v[126:127], 0, v[128:129]
	global_store_dwordx2 v[126:127], v[134:135], off
	v_cndmask_b32_e64 v134, v205, v213, s[40:41]
	v_cndmask_b32_e64 v135, v207, v215, s[40:41]
	v_cndmask_b32_e64 v138, v206, v216, s[40:41]
	v_cndmask_b32_e64 v139, v208, v218, s[40:41]
	v_pk_fma_f32 v[134:135], v[154:155], v[134:135], v[158:159]
	s_waitcnt lgkmcnt(4)
	v_cndmask_b32_e64 v145, v219, v223, s[42:43]
	v_cndmask_b32_e64 v144, v214, v221, s[42:43]
	v_pk_fma_f32 v[138:139], v[156:157], v[138:139], v[160:161]
	v_pk_fma_f32 v[130:131], v[130:131], v[150:151], v[134:135]
	v_cndmask_b32_e64 v141, v223, v163, s[42:43]
	v_cndmask_b32_e64 v140, v221, v162, s[42:43]
	s_waitcnt lgkmcnt(0)
	v_cndmask_b32_e64 v163, v220, v250, s[42:43]
	v_cndmask_b32_e64 v162, v217, v222, s[42:43]
	v_pk_fma_f32 v[132:133], v[132:133], v[152:153], v[138:139]
	v_pk_fma_f32 v[130:131], v[146:147], v[144:145], v[130:131]
	v_pk_fma_f32 v[132:133], v[148:149], v[162:163], v[132:133]
	v_pk_mul_f32 v[134:135], v[130:131], s[100:101] op_sel_hi:[1,0]
	v_exp_f32_e32 v134, v134
	v_exp_f32_e32 v135, v135
	v_pk_mul_f32 v[138:139], v[132:133], s[100:101] op_sel_hi:[1,0]
	v_exp_f32_e32 v138, v138
	v_exp_f32_e32 v139, v139
	v_pk_add_f32 v[134:135], v[134:135], 1.0 op_sel_hi:[1,0]
	v_rcp_f32_e32 v134, v134
	v_rcp_f32_e32 v135, v135
	v_pk_add_f32 v[138:139], v[138:139], 1.0 op_sel_hi:[1,0]
	v_rcp_f32_e32 v138, v138
	v_rcp_f32_e32 v139, v139
	v_pk_mul_f32 v[130:131], v[130:131], v[134:135]
	v_or_b32_e32 v144, 32, v204
	v_pk_mul_f32 v[122:123], v[122:123], v[130:131]
	v_pk_mul_f32 v[130:131], v[132:133], v[138:139]
	v_cndmask_b32_e64 v143, v250, v165, s[42:43]
	v_pk_mul_f32 v[124:125], v[124:125], v[130:131]
	v_cvt_pk_bf16_f32 v130, v122, v123
	v_mad_i64_i32 v[122:123], s[0:1], v144, s18, v[136:137]
	v_cvt_pk_bf16_f32 v131, v124, v125
	v_lshl_add_u64 v[122:123], v[122:123], 0, v[128:129]
	global_store_dwordx2 v[122:123], v[130:131], off
	v_cndmask_b32_e64 v125, v211, v207, s[40:41]
	v_cndmask_b32_e64 v124, v209, v205, s[40:41]
	v_cndmask_b32_e64 v131, v212, v208, s[40:41]
	v_cndmask_b32_e64 v130, v210, v206, s[40:41]
	v_pk_fma_f32 v[130:131], v[156:157], v[130:131], v[160:161]
	v_pk_fma_f32 v[124:125], v[154:155], v[124:125], v[158:159]
	v_cndmask_b32_e64 v142, v222, v164, s[42:43]
	v_pk_fma_f32 v[114:115], v[114:115], v[150:151], v[124:125]
	v_pk_fma_f32 v[116:117], v[116:117], v[152:153], v[130:131]
	v_pk_fma_f32 v[114:115], v[146:147], v[140:141], v[114:115]
	v_pk_fma_f32 v[116:117], v[148:149], v[142:143], v[116:117]
	v_pk_mul_f32 v[124:125], v[114:115], s[100:101] op_sel_hi:[1,0]
	v_pk_mul_f32 v[130:131], v[116:117], s[100:101] op_sel_hi:[1,0]
	v_exp_f32_e32 v124, v124
	v_exp_f32_e32 v125, v125
	v_exp_f32_e32 v130, v130
	v_exp_f32_e32 v131, v131
	v_pk_add_f32 v[124:125], v[124:125], 1.0 op_sel_hi:[1,0]
	v_pk_add_f32 v[130:131], v[130:131], 1.0 op_sel_hi:[1,0]
	v_rcp_f32_e32 v124, v124
	v_rcp_f32_e32 v125, v125
	v_rcp_f32_e32 v130, v130
	v_rcp_f32_e32 v131, v131
	v_or_b32_e32 v132, 48, v204
	v_pk_mul_f32 v[114:115], v[114:115], v[124:125]
	s_andn2_b64 vcc, exec, s[70:71]
	v_pk_mul_f32 v[116:117], v[116:117], v[130:131]
	v_pk_mul_f32 v[114:115], v[118:119], v[114:115]
	v_pk_mul_f32 v[116:117], v[120:121], v[116:117]
	v_cvt_pk_bf16_f32 v114, v114, v115
	v_cvt_pk_bf16_f32 v115, v116, v117
	v_mad_i64_i32 v[116:117], s[0:1], v132, s18, v[136:137]
	v_lshl_add_u64 v[124:125], v[116:117], 0, v[128:129]
	global_store_dwordx2 v[124:125], v[114:115], off
	v_cndmask_b32_e64 v115, 0, 1, s[70:71]
	v_mov_b32_e32 v114, 0
	v_cmp_ne_u32_e64 s[52:53], 1, v115
	v_mov_b32_e32 v118, 0
	v_mov_b32_e32 v119, 0
	v_mov_b32_e32 v120, 0
	v_mov_b32_e32 v121, 0
	s_cbranch_vccnz .LBB0_735
	ds_read_b128 v[118:121], v187 offset:1536

.LBB0_737:
	ds_bpermute_b32 v136, v202, v108
	ds_bpermute_b32 v137, v202, v109
	ds_bpermute_b32 v134, v202, v106
	ds_bpermute_b32 v135, v202, v107
	ds_bpermute_b32 v132, v203, v108
	ds_bpermute_b32 v133, v203, v109
	ds_bpermute_b32 v143, v203, v104
	ds_bpermute_b32 v145, v203, v105
	ds_bpermute_b32 v130, v203, v106
	ds_bpermute_b32 v131, v203, v107
	ds_bpermute_b32 v139, v203, v102
	ds_bpermute_b32 v141, v203, v103
	s_waitcnt lgkmcnt(10)
	v_cndmask_b32_e64 v121, v137, v121, s[40:41]
	v_cndmask_b32_e64 v120, v136, v120, s[40:41]
	s_waitcnt lgkmcnt(8)
	v_cndmask_b32_e64 v119, v135, v119, s[40:41]
	v_cndmask_b32_e64 v118, v134, v118, s[40:41]
	v_pk_fma_f32 v[120:121], v[156:157], v[120:121], v[160:161]
	s_waitcnt lgkmcnt(4)
	v_cndmask_b32_e64 v133, v133, v145, s[42:43]
	v_cndmask_b32_e64 v132, v132, v143, s[42:43]
	v_pk_fma_f32 v[118:119], v[154:155], v[118:119], v[158:159]
	v_pk_fma_f32 v[108:109], v[108:109], v[152:153], v[120:121]
	s_waitcnt lgkmcnt(0)
	v_cndmask_b32_e64 v131, v131, v141, s[42:43]
	v_cndmask_b32_e64 v130, v130, v139, s[42:43]
	v_pk_fma_f32 v[106:107], v[106:107], v[150:151], v[118:119]
	v_pk_fma_f32 v[108:109], v[148:149], v[132:133], v[108:109]
	v_pk_fma_f32 v[106:107], v[146:147], v[130:131], v[106:107]
	v_pk_mul_f32 v[120:121], v[108:109], s[100:101] op_sel_hi:[1,0]
	v_pk_mul_f32 v[118:119], v[106:107], s[100:101] op_sel_hi:[1,0]
	v_exp_f32_e32 v120, v120
	v_exp_f32_e32 v121, v121
	v_exp_f32_e32 v118, v118
	v_exp_f32_e32 v119, v119
	v_pk_add_f32 v[120:121], v[120:121], 1.0 op_sel_hi:[1,0]
	v_pk_add_f32 v[118:119], v[118:119], 1.0 op_sel_hi:[1,0]
	v_rcp_f32_e32 v120, v120
	v_rcp_f32_e32 v121, v121
	v_rcp_f32_e32 v118, v118
	v_rcp_f32_e32 v119, v119
	ds_bpermute_b32 v138, v202, v102
	ds_bpermute_b32 v140, v202, v103
	v_pk_mul_f32 v[108:109], v[108:109], v[120:121]
	ds_bpermute_b32 v142, v202, v104
	ds_bpermute_b32 v144, v202, v105
	v_pk_mul_f32 v[106:107], v[106:107], v[118:119]
	v_pk_mul_f32 v[108:109], v[112:113], v[108:109]
	ds_bpermute_b32 v163, v203, v94
	ds_bpermute_b32 v165, v203, v95
	v_add_u32_e32 v130, 0x80, v204
	v_pk_mul_f32 v[106:107], v[110:111], v[106:107]
	v_cvt_pk_bf16_f32 v111, v108, v109
	v_mov_b64_e32 v[108:109], s[22:23]
	ds_bpermute_b32 v167, v203, v96
	ds_bpermute_b32 v169, v203, v97
	v_cvt_pk_bf16_f32 v110, v106, v107
	v_mad_i64_i32 v[106:107], s[0:1], v130, s18, v[108:109]
	v_lshl_add_u64 v[106:107], v[106:107], 0, v[128:129]
	global_store_dwordx2 v[106:107], v[110:111], off
	s_waitcnt lgkmcnt(6)
	v_cndmask_b32_e64 v111, v140, v135, s[40:41]
	v_cndmask_b32_e64 v110, v138, v134, s[40:41]
	s_waitcnt lgkmcnt(4)
	v_cndmask_b32_e64 v113, v144, v137, s[40:41]
	v_cndmask_b32_e64 v112, v142, v136, s[40:41]
	v_pk_fma_f32 v[110:111], v[154:155], v[110:111], v[158:159]
	s_waitcnt lgkmcnt(3)
	v_cndmask_b32_e64 v118, v139, v163, s[42:43]
	s_waitcnt lgkmcnt(2)
	v_cndmask_b32_e64 v119, v141, v165, s[42:43]
	v_pk_fma_f32 v[112:113], v[156:157], v[112:113], v[160:161]
	v_pk_fma_f32 v[102:103], v[102:103], v[150:151], v[110:111]
	s_waitcnt lgkmcnt(1)
	v_cndmask_b32_e64 v120, v143, v167, s[42:43]
	s_waitcnt lgkmcnt(0)
	v_cndmask_b32_e64 v121, v145, v169, s[42:43]
	v_pk_fma_f32 v[104:105], v[104:105], v[152:153], v[112:113]
	v_pk_fma_f32 v[102:103], v[146:147], v[118:119], v[102:103]
	v_pk_fma_f32 v[104:105], v[148:149], v[120:121], v[104:105]
	v_pk_mul_f32 v[110:111], v[102:103], s[100:101] op_sel_hi:[1,0]
	v_exp_f32_e32 v110, v110
	v_exp_f32_e32 v111, v111
	v_pk_mul_f32 v[112:113], v[104:105], s[100:101] op_sel_hi:[1,0]
	v_exp_f32_e32 v112, v112
	v_exp_f32_e32 v113, v113
	v_pk_add_f32 v[110:111], v[110:111], 1.0 op_sel_hi:[1,0]
	v_rcp_f32_e32 v110, v110
	v_rcp_f32_e32 v111, v111
	v_pk_add_f32 v[112:113], v[112:113], 1.0 op_sel_hi:[1,0]
	v_rcp_f32_e32 v112, v112
	v_rcp_f32_e32 v113, v113
	ds_bpermute_b32 v162, v202, v94
	ds_bpermute_b32 v164, v202, v95
	ds_bpermute_b32 v166, v202, v96
	ds_bpermute_b32 v168, v202, v97
	ds_bpermute_b32 v181, v203, v66
	ds_bpermute_b32 v195, v203, v67
	v_pk_mul_f32 v[102:103], v[102:103], v[110:111]
	ds_bpermute_b32 v197, v203, v68
	ds_bpermute_b32 v206, v203, v69
	v_add_u32_e32 v118, 0x90, v204
	v_pk_mul_f32 v[98:99], v[98:99], v[102:103]
	v_pk_mul_f32 v[102:103], v[104:105], v[112:113]
	s_waitcnt lgkmcnt(3)
	v_cndmask_b32_e64 v104, v163, v181, s[42:43]
	v_pk_mul_f32 v[100:101], v[100:101], v[102:103]
	v_cvt_pk_bf16_f32 v102, v98, v99
	v_mad_i64_i32 v[98:99], s[0:1], v118, s18, v[108:109]
	v_cvt_pk_bf16_f32 v103, v100, v101
	v_lshl_add_u64 v[98:99], v[98:99], 0, v[128:129]
	v_cndmask_b32_e64 v101, v164, v140, s[40:41]
	v_cndmask_b32_e64 v100, v162, v138, s[40:41]
	global_store_dwordx2 v[98:99], v[102:103], off
	v_cndmask_b32_e64 v103, v168, v144, s[40:41]
	v_cndmask_b32_e64 v102, v166, v142, s[40:41]
	v_pk_fma_f32 v[100:101], v[154:155], v[100:101], v[158:159]
	s_waitcnt lgkmcnt(2)
	v_cndmask_b32_e64 v105, v165, v195, s[42:43]
	v_pk_fma_f32 v[102:103], v[156:157], v[102:103], v[160:161]
	v_pk_fma_f32 v[94:95], v[94:95], v[150:151], v[100:101]
	s_waitcnt lgkmcnt(1)
	v_cndmask_b32_e64 v110, v167, v197, s[42:43]
	s_waitcnt lgkmcnt(0)
	v_cndmask_b32_e64 v111, v169, v206, s[42:43]
	v_pk_fma_f32 v[96:97], v[96:97], v[152:153], v[102:103]
	v_pk_fma_f32 v[94:95], v[146:147], v[104:105], v[94:95]
	v_pk_fma_f32 v[96:97], v[148:149], v[110:111], v[96:97]
	v_pk_mul_f32 v[100:101], v[94:95], s[100:101] op_sel_hi:[1,0]
	v_exp_f32_e32 v100, v100
	v_exp_f32_e32 v101, v101
	v_pk_mul_f32 v[102:103], v[96:97], s[100:101] op_sel_hi:[1,0]
	v_exp_f32_e32 v102, v102
	v_exp_f32_e32 v103, v103
	v_pk_add_f32 v[100:101], v[100:101], 1.0 op_sel_hi:[1,0]
	v_rcp_f32_e32 v100, v100
	v_rcp_f32_e32 v101, v101
	v_pk_add_f32 v[102:103], v[102:103], 1.0 op_sel_hi:[1,0]
	v_rcp_f32_e32 v102, v102
	v_rcp_f32_e32 v103, v103
	ds_bpermute_b32 v180, v202, v66
	ds_bpermute_b32 v194, v202, v67
	v_pk_mul_f32 v[94:95], v[94:95], v[100:101]
	ds_bpermute_b32 v196, v202, v68
	ds_bpermute_b32 v205, v202, v69
	v_pk_mul_f32 v[90:91], v[90:91], v[94:95]
	v_pk_mul_f32 v[94:95], v[96:97], v[102:103]
	v_add_u32_e32 v104, 0xa0, v204
	v_pk_mul_f32 v[92:93], v[92:93], v[94:95]
	v_cvt_pk_bf16_f32 v90, v90, v91
	v_cvt_pk_bf16_f32 v91, v92, v93
	v_mad_i64_i32 v[92:93], s[0:1], v104, s18, v[108:109]
	v_lshl_add_u64 v[94:95], v[92:93], 0, v[128:129]
	global_store_dwordx2 v[94:95], v[90:91], off
	s_waitcnt lgkmcnt(2)
	v_cndmask_b32_e64 v91, v194, v164, s[40:41]
	v_cndmask_b32_e64 v90, v180, v162, s[40:41]
	s_waitcnt lgkmcnt(0)
	v_cndmask_b32_e64 v93, v205, v168, s[40:41]
	v_cndmask_b32_e64 v92, v196, v166, s[40:41]
	v_pk_fma_f32 v[90:91], v[154:155], v[90:91], v[158:159]
	v_cndmask_b32_e64 v97, v195, v115, s[42:43]
	v_cndmask_b32_e64 v96, v181, v114, s[42:43]
	v_pk_fma_f32 v[92:93], v[156:157], v[92:93], v[160:161]
	v_pk_fma_f32 v[90:91], v[66:67], v[150:151], v[90:91]
	v_cndmask_b32_e64 v101, v206, v117, s[42:43]
	v_cndmask_b32_e64 v100, v197, v116, s[42:43]
	v_pk_fma_f32 v[92:93], v[68:69], v[152:153], v[92:93]
	v_pk_fma_f32 v[90:91], v[146:147], v[96:97], v[90:91]
	v_pk_fma_f32 v[92:93], v[148:149], v[100:101], v[92:93]
	v_pk_mul_f32 v[96:97], v[90:91], s[100:101] op_sel_hi:[1,0]
	v_exp_f32_e32 v96, v96
	v_exp_f32_e32 v97, v97
	v_pk_mul_f32 v[100:101], v[92:93], s[100:101] op_sel_hi:[1,0]
	v_exp_f32_e32 v100, v100
	v_exp_f32_e32 v101, v101
	v_pk_add_f32 v[96:97], v[96:97], 1.0 op_sel_hi:[1,0]
	v_rcp_f32_e32 v96, v96
	v_rcp_f32_e32 v97, v97
	v_pk_add_f32 v[100:101], v[100:101], 1.0 op_sel_hi:[1,0]
	v_rcp_f32_e32 v100, v100
	v_rcp_f32_e32 v101, v101
	v_pk_mul_f32 v[96:97], v[90:91], v[96:97]
	v_add_u32_e32 v104, 0xb0, v204
	v_pk_mul_f32 v[96:97], v[70:71], v[96:97]
	v_pk_mul_f32 v[100:101], v[92:93], v[100:101]
	v_cvt_pk_bf16_f32 v102, v96, v97
	v_pk_mul_f32 v[100:101], v[72:73], v[100:101]
	v_mad_i64_i32 v[96:97], s[0:1], v104, s18, v[108:109]
	v_cvt_pk_bf16_f32 v103, v100, v101
	v_lshl_add_u64 v[96:97], v[96:97], 0, v[128:129]
	global_store_dwordx2 v[96:97], v[102:103], off
	s_and_saveexec_b64 s[20:21], s[74:75]
	s_cbranch_execz .LBB0_739
	v_add_co_u32_e32 v100, vcc, 0x8000, v176
	s_nop 1
	v_addc_co_u32_e32 v101, vcc, 0, v177, vcc
	global_store_dwordx4 v[100:101], v[90:93], off offset:1024
	s_nop 1
	v_add_co_u32_e32 v90, vcc, 0xb000, v176
	s_nop 1
	v_addc_co_u32_e32 v91, vcc, 0, v177, vcc
	global_store_dwordx4 v[90:91], v[70:73], off
	s_nop 1
	v_add_co_u32_e32 v70, vcc, 0xd000, v176
	s_nop 1
	v_addc_co_u32_e32 v71, vcc, 0, v177, vcc
	global_store_dwordx4 v[70:71], v[66:69], off offset:3072

.LBB0_745:
	s_or_b64 exec, exec, s[20:21]
	s_waitcnt lgkmcnt(14)
	v_cndmask_b32_e64 v46, v105, v117, s[40:41]
	v_cndmask_b32_e64 v47, v109, v118, s[40:41]
	v_cndmask_b32_e64 v48, v110, v119, s[40:41]
	v_cndmask_b32_e64 v49, v112, v120, s[40:41]
	v_pk_fma_f32 v[48:49], v[84:85], v[48:49], v[88:89]
	v_pk_fma_f32 v[46:47], v[82:83], v[46:47], v[86:87]
	s_waitcnt lgkmcnt(12)
	v_cndmask_b32_e64 v63, v129, v113, s[42:43]
	v_cndmask_b32_e64 v62, v121, v108, s[42:43]
	s_waitcnt lgkmcnt(8)
	v_cndmask_b32_e64 v65, v130, v114, s[42:43]
	v_cndmask_b32_e64 v64, v128, v111, s[42:43]
	v_pk_fma_f32 v[46:47], v[58:59], v[78:79], v[46:47]
	v_pk_fma_f32 v[48:49], v[60:61], v[80:81], v[48:49]
	v_pk_fma_f32 v[46:47], v[74:75], v[62:63], v[46:47]
	v_pk_fma_f32 v[48:49], v[76:77], v[64:65], v[48:49]
	v_pk_mul_f32 v[58:59], v[46:47], s[100:101] op_sel_hi:[1,0]
	v_pk_mul_f32 v[60:61], v[48:49], s[100:101] op_sel_hi:[1,0]
	v_exp_f32_e32 v58, v58
	v_exp_f32_e32 v59, v59
	v_exp_f32_e32 v60, v60
	v_exp_f32_e32 v61, v61
	v_pk_add_f32 v[58:59], v[58:59], 1.0 op_sel_hi:[1,0]
	v_pk_add_f32 v[60:61], v[60:61], 1.0 op_sel_hi:[1,0]
	v_rcp_f32_e32 v58, v58
	v_rcp_f32_e32 v59, v59
	v_rcp_f32_e32 v60, v60
	v_rcp_f32_e32 v61, v61
	s_and_b64 vcc, exec, s[52:53]
	v_pk_mul_f32 v[46:47], v[46:47], v[58:59]
	s_waitcnt lgkmcnt(4)
	v_cndmask_b32_e64 v59, v113, v116, s[42:43]
	v_pk_mul_f32 v[48:49], v[48:49], v[60:61]
	v_pk_mul_f32 v[46:47], v[54:55], v[46:47]
	v_pk_mul_f32 v[48:49], v[56:57], v[48:49]
	v_cvt_pk_bf16_f32 v46, v46, v47
	v_cvt_pk_bf16_f32 v47, v48, v49
	global_store_dwordx2 v[126:127], v[46:47], off offset:8
	v_cndmask_b32_e64 v46, v90, v105, s[40:41]
	v_cndmask_b32_e64 v47, v92, v109, s[40:41]
	v_cndmask_b32_e64 v48, v91, v110, s[40:41]
	v_cndmask_b32_e64 v49, v93, v112, s[40:41]
	v_pk_fma_f32 v[46:47], v[82:83], v[46:47], v[86:87]
	v_cndmask_b32_e64 v58, v108, v115, s[42:43]
	v_pk_fma_f32 v[48:49], v[84:85], v[48:49], v[88:89]
	v_pk_fma_f32 v[46:47], v[50:51], v[78:79], v[46:47]
	s_waitcnt lgkmcnt(0)
	v_cndmask_b32_e64 v61, v114, v131, s[42:43]
	v_cndmask_b32_e64 v60, v111, v104, s[42:43]
	v_pk_fma_f32 v[48:49], v[52:53], v[80:81], v[48:49]
	v_pk_fma_f32 v[46:47], v[74:75], v[58:59], v[46:47]
	v_pk_fma_f32 v[48:49], v[76:77], v[60:61], v[48:49]
	v_pk_mul_f32 v[50:51], v[46:47], s[100:101] op_sel_hi:[1,0]
	v_exp_f32_e32 v50, v50
	v_exp_f32_e32 v51, v51
	v_pk_mul_f32 v[52:53], v[48:49], s[100:101] op_sel_hi:[1,0]
	v_exp_f32_e32 v52, v52
	v_exp_f32_e32 v53, v53
	v_pk_add_f32 v[50:51], v[50:51], 1.0 op_sel_hi:[1,0]
	v_rcp_f32_e32 v50, v50
	v_rcp_f32_e32 v51, v51
	v_pk_add_f32 v[52:53], v[52:53], 1.0 op_sel_hi:[1,0]
	v_rcp_f32_e32 v52, v52
	v_rcp_f32_e32 v53, v53
	v_pk_mul_f32 v[46:47], v[46:47], v[50:51]
	v_cndmask_b32_e64 v55, v116, v67, s[42:43]
	v_pk_mul_f32 v[42:43], v[42:43], v[46:47]
	v_pk_mul_f32 v[46:47], v[48:49], v[52:53]
	v_cvt_pk_bf16_f32 v42, v42, v43
	v_pk_mul_f32 v[44:45], v[44:45], v[46:47]
	v_cndmask_b32_e64 v47, v103, v93, s[40:41]
	v_cvt_pk_bf16_f32 v43, v44, v45
	v_cndmask_b32_e64 v45, v102, v92, s[40:41]
	v_cndmask_b32_e64 v44, v100, v90, s[40:41]
	v_cndmask_b32_e64 v46, v101, v91, s[40:41]
	v_pk_fma_f32 v[46:47], v[84:85], v[46:47], v[88:89]
	v_pk_fma_f32 v[44:45], v[82:83], v[44:45], v[86:87]
	v_cndmask_b32_e64 v54, v115, v66, s[42:43]
	v_cndmask_b32_e64 v57, v131, v69, s[42:43]
	v_cndmask_b32_e64 v56, v104, v68, s[42:43]
	v_pk_fma_f32 v[34:35], v[34:35], v[78:79], v[44:45]
	v_pk_fma_f32 v[36:37], v[36:37], v[80:81], v[46:47]
	v_pk_fma_f32 v[34:35], v[74:75], v[54:55], v[34:35]
	v_pk_fma_f32 v[36:37], v[76:77], v[56:57], v[36:37]
	v_pk_mul_f32 v[44:45], v[34:35], s[100:101] op_sel_hi:[1,0]
	v_pk_mul_f32 v[46:47], v[36:37], s[100:101] op_sel_hi:[1,0]
	v_exp_f32_e32 v44, v44
	v_exp_f32_e32 v45, v45
	v_exp_f32_e32 v46, v46
	v_exp_f32_e32 v47, v47
	v_pk_add_f32 v[44:45], v[44:45], 1.0 op_sel_hi:[1,0]
	v_pk_add_f32 v[46:47], v[46:47], 1.0 op_sel_hi:[1,0]
	v_rcp_f32_e32 v44, v44
	v_rcp_f32_e32 v45, v45
	v_rcp_f32_e32 v46, v46
	v_rcp_f32_e32 v47, v47
	global_store_dwordx2 v[122:123], v[42:43], off offset:8
	v_pk_mul_f32 v[34:35], v[34:35], v[44:45]
	v_pk_mul_f32 v[36:37], v[36:37], v[46:47]
	v_pk_mul_f32 v[34:35], v[38:39], v[34:35]
	v_pk_mul_f32 v[36:37], v[40:41], v[36:37]
	v_cvt_pk_bf16_f32 v34, v34, v35
	v_cvt_pk_bf16_f32 v35, v36, v37
	global_store_dwordx2 v[124:125], v[34:35], off offset:8
	v_mov_b32_e32 v34, 0
	v_mov_b32_e32 v38, 0
	v_mov_b32_e32 v39, 0
	v_mov_b32_e32 v40, 0
	v_mov_b32_e32 v41, 0
	s_cbranch_vccnz .LBB0_747
	ds_read_b128 v[38:41], v187 offset:1552

.LBB0_749:
	ds_bpermute_b32 v46, v202, v30
	ds_bpermute_b32 v47, v202, v31
	ds_bpermute_b32 v48, v202, v32
	ds_bpermute_b32 v49, v202, v33
	ds_bpermute_b32 v42, v203, v30
	ds_bpermute_b32 v43, v203, v31
	ds_bpermute_b32 v51, v203, v22
	ds_bpermute_b32 v53, v203, v23
	ds_bpermute_b32 v44, v203, v32
	ds_bpermute_b32 v45, v203, v33
	ds_bpermute_b32 v55, v203, v24
	ds_bpermute_b32 v57, v203, v25
	s_waitcnt lgkmcnt(10)
	v_cndmask_b32_e64 v39, v47, v39, s[40:41]
	v_cndmask_b32_e64 v38, v46, v38, s[40:41]
	s_waitcnt lgkmcnt(8)
	v_cndmask_b32_e64 v41, v49, v41, s[40:41]
	v_cndmask_b32_e64 v40, v48, v40, s[40:41]
	v_pk_fma_f32 v[38:39], v[82:83], v[38:39], v[86:87]
	s_waitcnt lgkmcnt(4)
	v_cndmask_b32_e64 v43, v43, v53, s[42:43]
	v_cndmask_b32_e64 v42, v42, v51, s[42:43]
	v_pk_fma_f32 v[40:41], v[84:85], v[40:41], v[88:89]
	v_pk_fma_f32 v[30:31], v[30:31], v[78:79], v[38:39]
	s_waitcnt lgkmcnt(0)
	v_cndmask_b32_e64 v45, v45, v57, s[42:43]
	v_cndmask_b32_e64 v44, v44, v55, s[42:43]
	v_pk_fma_f32 v[32:33], v[32:33], v[80:81], v[40:41]
	v_pk_fma_f32 v[30:31], v[74:75], v[42:43], v[30:31]
	v_pk_fma_f32 v[32:33], v[76:77], v[44:45], v[32:33]
	v_pk_mul_f32 v[38:39], v[30:31], s[100:101] op_sel_hi:[1,0]
	v_exp_f32_e32 v38, v38
	v_exp_f32_e32 v39, v39
	v_pk_mul_f32 v[40:41], v[32:33], s[100:101] op_sel_hi:[1,0]
	v_exp_f32_e32 v40, v40
	v_exp_f32_e32 v41, v41
	v_pk_add_f32 v[38:39], v[38:39], 1.0 op_sel_hi:[1,0]
	v_rcp_f32_e32 v38, v38
	v_rcp_f32_e32 v39, v39
	v_pk_add_f32 v[40:41], v[40:41], 1.0 op_sel_hi:[1,0]
	v_rcp_f32_e32 v40, v40
	v_rcp_f32_e32 v41, v41
	ds_bpermute_b32 v50, v202, v22
	ds_bpermute_b32 v52, v202, v23
	ds_bpermute_b32 v54, v202, v24
	ds_bpermute_b32 v56, v202, v25
	ds_bpermute_b32 v59, v203, v14
	ds_bpermute_b32 v61, v203, v15
	v_pk_mul_f32 v[30:31], v[30:31], v[38:39]
	ds_bpermute_b32 v63, v203, v16
	ds_bpermute_b32 v65, v203, v17
	v_pk_mul_f32 v[26:27], v[26:27], v[30:31]
	v_pk_mul_f32 v[30:31], v[32:33], v[40:41]
	v_cvt_pk_bf16_f32 v26, v26, v27
	v_pk_mul_f32 v[28:29], v[28:29], v[30:31]
	s_waitcnt lgkmcnt(4)
	v_cndmask_b32_e64 v31, v56, v49, s[40:41]
	v_cvt_pk_bf16_f32 v27, v28, v29
	v_cndmask_b32_e64 v29, v52, v47, s[40:41]
	v_cndmask_b32_e64 v28, v50, v46, s[40:41]
	v_cndmask_b32_e64 v30, v54, v48, s[40:41]
	v_pk_fma_f32 v[28:29], v[82:83], v[28:29], v[86:87]
	s_waitcnt lgkmcnt(3)
	v_cndmask_b32_e64 v32, v51, v59, s[42:43]
	s_waitcnt lgkmcnt(2)
	v_cndmask_b32_e64 v33, v53, v61, s[42:43]
	v_pk_fma_f32 v[30:31], v[84:85], v[30:31], v[88:89]
	v_pk_fma_f32 v[22:23], v[22:23], v[78:79], v[28:29]
	s_waitcnt lgkmcnt(1)
	v_cndmask_b32_e64 v38, v55, v63, s[42:43]
	s_waitcnt lgkmcnt(0)
	v_cndmask_b32_e64 v39, v57, v65, s[42:43]
	v_pk_fma_f32 v[24:25], v[24:25], v[80:81], v[30:31]
	v_pk_fma_f32 v[22:23], v[74:75], v[32:33], v[22:23]
	v_pk_fma_f32 v[24:25], v[76:77], v[38:39], v[24:25]
	v_pk_mul_f32 v[28:29], v[22:23], s[100:101] op_sel_hi:[1,0]
	v_exp_f32_e32 v28, v28
	v_exp_f32_e32 v29, v29
	v_pk_mul_f32 v[30:31], v[24:25], s[100:101] op_sel_hi:[1,0]
	v_exp_f32_e32 v30, v30
	v_exp_f32_e32 v31, v31
	v_pk_add_f32 v[28:29], v[28:29], 1.0 op_sel_hi:[1,0]
	v_rcp_f32_e32 v28, v28
	v_rcp_f32_e32 v29, v29
	v_pk_add_f32 v[30:31], v[30:31], 1.0 op_sel_hi:[1,0]
	v_rcp_f32_e32 v30, v30
	v_rcp_f32_e32 v31, v31
	ds_bpermute_b32 v58, v202, v14
	ds_bpermute_b32 v60, v202, v15
	ds_bpermute_b32 v62, v202, v16
	ds_bpermute_b32 v64, v202, v17
	ds_bpermute_b32 v67, v203, v2
	ds_bpermute_b32 v69, v203, v3
	v_pk_mul_f32 v[22:23], v[22:23], v[28:29]
	ds_bpermute_b32 v71, v203, v4
	ds_bpermute_b32 v42, v203, v5
	v_pk_mul_f32 v[18:19], v[18:19], v[22:23]
	v_pk_mul_f32 v[22:23], v[24:25], v[30:31]
	v_cvt_pk_bf16_f32 v18, v18, v19
	v_pk_mul_f32 v[20:21], v[20:21], v[22:23]
	s_waitcnt lgkmcnt(4)
	v_cndmask_b32_e64 v23, v64, v56, s[40:41]
	v_cvt_pk_bf16_f32 v19, v20, v21
	v_cndmask_b32_e64 v21, v60, v52, s[40:41]
	v_cndmask_b32_e64 v20, v58, v50, s[40:41]
	v_cndmask_b32_e64 v22, v62, v54, s[40:41]
	v_pk_fma_f32 v[20:21], v[82:83], v[20:21], v[86:87]
	s_waitcnt lgkmcnt(3)
	v_cndmask_b32_e64 v24, v59, v67, s[42:43]
	s_waitcnt lgkmcnt(2)
	v_cndmask_b32_e64 v25, v61, v69, s[42:43]
	v_pk_fma_f32 v[22:23], v[84:85], v[22:23], v[88:89]
	v_pk_fma_f32 v[14:15], v[14:15], v[78:79], v[20:21]
	global_store_dwordx2 v[106:107], v[26:27], off offset:8
	s_waitcnt lgkmcnt(1)
	v_cndmask_b32_e64 v26, v63, v71, s[42:43]
	s_waitcnt lgkmcnt(0)
	v_cndmask_b32_e64 v27, v65, v42, s[42:43]
	v_pk_fma_f32 v[16:17], v[16:17], v[80:81], v[22:23]
	v_pk_fma_f32 v[14:15], v[74:75], v[24:25], v[14:15]
	v_pk_fma_f32 v[16:17], v[76:77], v[26:27], v[16:17]
	v_pk_mul_f32 v[20:21], v[14:15], s[100:101] op_sel_hi:[1,0]
	v_exp_f32_e32 v20, v20
	v_exp_f32_e32 v21, v21
	v_pk_mul_f32 v[22:23], v[16:17], s[100:101] op_sel_hi:[1,0]
	v_exp_f32_e32 v22, v22
	v_exp_f32_e32 v23, v23
	v_pk_add_f32 v[20:21], v[20:21], 1.0 op_sel_hi:[1,0]
	v_rcp_f32_e32 v20, v20
	v_rcp_f32_e32 v21, v21
	v_pk_add_f32 v[22:23], v[22:23], 1.0 op_sel_hi:[1,0]
	v_rcp_f32_e32 v22, v22
	v_rcp_f32_e32 v23, v23
	ds_bpermute_b32 v66, v202, v2
	ds_bpermute_b32 v68, v202, v3
	ds_bpermute_b32 v70, v202, v4
	ds_bpermute_b32 v72, v202, v5
	v_pk_mul_f32 v[14:15], v[14:15], v[20:21]
	global_store_dwordx2 v[98:99], v[18:19], off offset:8
	v_pk_mul_f32 v[10:11], v[10:11], v[14:15]
	v_pk_mul_f32 v[14:15], v[16:17], v[22:23]
	v_cndmask_b32_e64 v17, v69, v35, s[42:43]
	v_pk_mul_f32 v[12:13], v[12:13], v[14:15]
	v_cvt_pk_bf16_f32 v14, v10, v11
	v_cvt_pk_bf16_f32 v15, v12, v13
	s_waitcnt lgkmcnt(2)
	v_cndmask_b32_e64 v11, v68, v60, s[40:41]
	v_cndmask_b32_e64 v10, v66, v58, s[40:41]
	s_waitcnt lgkmcnt(0)
	v_cndmask_b32_e64 v13, v72, v64, s[40:41]
	v_cndmask_b32_e64 v12, v70, v62, s[40:41]
	v_pk_fma_f32 v[12:13], v[84:85], v[12:13], v[88:89]
	v_pk_fma_f32 v[10:11], v[82:83], v[10:11], v[86:87]
	v_cndmask_b32_e64 v16, v67, v34, s[42:43]
	v_cndmask_b32_e64 v19, v42, v37, s[42:43]
	v_cndmask_b32_e64 v18, v71, v36, s[42:43]
	v_pk_fma_f32 v[10:11], v[2:3], v[78:79], v[10:11]
	v_pk_fma_f32 v[12:13], v[4:5], v[80:81], v[12:13]
	v_pk_fma_f32 v[10:11], v[74:75], v[16:17], v[10:11]
	v_pk_fma_f32 v[12:13], v[76:77], v[18:19], v[12:13]
	v_pk_mul_f32 v[16:17], v[10:11], s[100:101] op_sel_hi:[1,0]
	v_pk_mul_f32 v[18:19], v[12:13], s[100:101] op_sel_hi:[1,0]
	v_exp_f32_e32 v16, v16
	v_exp_f32_e32 v17, v17
	v_exp_f32_e32 v18, v18
	v_exp_f32_e32 v19, v19
	v_pk_add_f32 v[16:17], v[16:17], 1.0 op_sel_hi:[1,0]
	v_pk_add_f32 v[18:19], v[18:19], 1.0 op_sel_hi:[1,0]
	v_rcp_f32_e32 v16, v16
	v_rcp_f32_e32 v17, v17
	v_rcp_f32_e32 v18, v18
	v_rcp_f32_e32 v19, v19
	global_store_dwordx2 v[94:95], v[14:15], off offset:8
	v_pk_mul_f32 v[14:15], v[10:11], v[16:17]
	v_pk_mul_f32 v[16:17], v[12:13], v[18:19]
	v_pk_mul_f32 v[14:15], v[6:7], v[14:15]
	v_pk_mul_f32 v[16:17], v[8:9], v[16:17]
	v_cvt_pk_bf16_f32 v14, v14, v15
	v_cvt_pk_bf16_f32 v15, v16, v17
	global_store_dwordx2 v[96:97], v[14:15], off offset:8
	s_and_saveexec_b64 s[20:21], s[74:75]
	s_cbranch_execz .LBB0_701
	v_add_co_u32_e32 v14, vcc, 0x8000, v176
	s_nop 1
	v_addc_co_u32_e32 v15, vcc, 0, v177, vcc
	global_store_dwordx4 v[14:15], v[10:13], off offset:1040
	s_nop 1
	v_add_co_u32_e32 v10, vcc, 0xb000, v176
	s_nop 1
	v_addc_co_u32_e32 v11, vcc, 0, v177, vcc
	global_store_dwordx4 v[10:11], v[6:9], off offset:16
	s_nop 1
	v_add_co_u32_e32 v6, vcc, 0xd000, v176
	s_nop 1
	v_addc_co_u32_e32 v7, vcc, 0, v177, vcc
	global_store_dwordx4 v[6:7], v[2:5], off offset:3088
	s_branch .LBB0_701

.LBB0_877:
	s_and_b64 vcc, exec, s[2:3]
	s_cbranch_vccz .LBB0_1227
	v_readlane_b32 s0, v254, 1
	s_cmpk_gt_i32 s0, 0x1ff
	s_waitcnt vmcnt(0)
	v_ashrrev_i32_e32 v130, 3, v200
	s_movk_i32 s0, 0xffe0
	v_and_b32_e32 v167, 31, v200
	v_bfe_u32 v0, v200, 5, 1
	s_waitcnt vmcnt(0)
	v_and_b32_e32 v2, 7, v200
	v_bfi_b32 v137, s0, v130, v200
	s_movk_i32 s0, 0x90
	v_and_b32_e32 v135, 0xc0, v200
	v_lshlrev_b32_e32 v134, 3, v0
	v_ashrrev_i32_e32 v131, 31, v130
	v_lshlrev_b32_e32 v136, 3, v2
	v_lshlrev_b32_e32 v132, 4, v2
	v_mul_lo_u32 v166, v130, s0
	v_lshl_add_u32 v139, v0, 4, s36
	v_mul_u32_u24_e32 v155, 0x90, v167
	v_lshlrev_b32_e32 v138, 2, v0
	v_readlane_b32 s1, v254, 2
	s_cbranch_scc1 .LBB0_893
	s_add_u32 s0, s12, 0x13700000
	s_addc_u32 s1, s13, 0
	s_mul_i32 s7, s37, 0x480000
	s_mul_hi_i32 s6, s37, 0x480000
	s_add_u32 s4, s0, s7
	s_addc_u32 s8, s1, s6
	s_add_i32 s2, s37, 2
	s_add_i32 s3, s7, 0x900000
	s_mul_hi_i32 s2, s2, 0x480000
	s_add_u32 s0, s0, s3
	s_addc_u32 s1, s1, s2
	v_mov_b64_e32 v[2:3], s[0:1]
	s_movk_i32 s14, 0x1200
	v_mad_i64_i32 v[2:3], s[0:1], v130, s14, v[2:3]
	s_cmpk_eq_i32 s5, 0x100
	v_readlane_b32 s10, v254, 1
	v_mov_b32_e32 v133, v1
	s_movk_i32 s0, 0x88
	s_cselect_b64 s[2:3], -1, 0
	v_readlane_b32 s11, v254, 2
	s_mov_b32 s16, s10
	s_lshl_b32 s10, s10, 1
	v_lshl_add_u64 v[142:143], v[2:3], 0, v[132:133]
	v_mul_lo_u32 v2, v130, s0
	s_and_b32 s10, s10, 14
	s_ashr_i32 s11, s16, 3
	v_add_u32_e32 v169, s36, v2
	v_xor_b32_e32 v2, 32, v224
	v_add_u32_e32 v3, 64, v225
	v_cmp_lt_i32_e32 vcc, v2, v3
	s_add_u32 s0, s12, s7
	s_addc_u32 s1, s13, s6
	v_cndmask_b32_e32 v2, v224, v2, vcc
	v_lshlrev_b64 v[140:141], 8, v[130:131]
	v_add_u32_e32 v0, s36, v166
	v_add_u32_e32 v4, s36, v134
	v_mul_u32_u24_e32 v5, 0x88, v167
	v_lshlrev_b32_e32 v170, 2, v2
	v_mov_b64_e32 v[2:3], s[0:1]
	v_add_u32_e32 v168, 0x1000, v137
	v_mad_i64_i32 v[144:145], s[6:7], v130, s14, v[2:3]
	v_lshl_add_u64 v[146:147], s[0:1], 0, v[140:141]
	v_lshlrev_b32_e32 v148, 1, v134
	v_lshlrev_b32_e32 v150, 1, v136
	v_lshlrev_b32_e32 v152, 1, v138
	v_add_u32_e32 v171, v0, v132
	v_add_u32_e32 v172, v139, v155
	v_add_u32_e32 v173, v4, v5
	v_readfirstlane_b32 s0, v191
	s_cmpk_lt_u32 s0, 0x100
	s_cbranch_scc1 .Lattn_prio_skip
	s_setprio 1
.Lattn_prio_skip:
	s_branch .LBB0_881

.LBB0_893:
	s_setprio 0
	v_readlane_b32 s0, v254, 1
	s_cmpk_gt_i32 s0, 0x7f
	v_readlane_b32 s1, v254, 2
	s_cbranch_scc1 .LBB0_902
	v_lshlrev_b64 v[2:3], 9, v[130:131]
	v_lshl_add_u64 v[2:3], s[12:13], 0, v[2:3]
	v_mov_b32_e32 v133, v1
	v_lshl_add_u64 v[2:3], v[2:3], 0, v[132:133]
	s_mov_b64 s[0:1], 0xe700000
	v_lshlrev_b64 v[114:115], 8, v[130:131]
	v_lshl_add_u64 v[116:117], v[2:3], 0, s[0:1]
	s_mov_b64 s[0:1], 0x4000
	v_lshl_add_u64 v[118:119], v[114:115], 0, s[0:1]
	s_mov_b64 s[0:1], 0x8000
	v_lshl_add_u64 v[120:121], v[114:115], 0, s[0:1]
	s_mov_b64 s[0:1], 0xc000
	v_lshl_add_u64 v[122:123], v[114:115], 0, s[0:1]
	s_movk_i32 s0, 0x208
	v_xor_b32_e32 v5, 32, v224
	v_add_u32_e32 v6, 64, v225
	v_mul_lo_u32 v2, v130, s0
	v_cmp_lt_i32_e32 vcc, v5, v6
	s_add_u32 s2, s12, 0xe600000
	v_add_u32_e32 v0, s36, v132
	v_add_u32_e32 v2, s36, v2
	v_add_u32_e32 v3, s36, v134
	v_mul_u32_u24_e32 v4, 0x208, v167
	v_cndmask_b32_e32 v5, v224, v5, vcc
	v_readlane_b32 s0, v254, 1
	s_addc_u32 s3, s13, 0
	v_lshlrev_b32_e32 v131, 2, v5
	s_lshl_b32 s4, s0, 6
	s_lshl_b32 s6, s5, 6
	v_lshlrev_b32_e32 v124, 1, v134
	v_lshlrev_b32_e32 v126, 1, v136
	v_add_u32_e32 v134, v0, v166
	v_add_u32_e32 v136, v2, v132
	v_lshlrev_b32_e32 v128, 1, v138
	v_add_u32_e32 v138, v139, v155
	v_add_u32_e32 v139, v3, v4
	s_mov_b32 s7, s0
	v_readlane_b32 s1, v254, 2
	s_branch .LBB0_896

	.amdhsa_kernel _Z6mk_fwd6Params
		.amdhsa_group_segment_fixed_size 0
		.amdhsa_private_segment_fixed_size 0
		.amdhsa_kernarg_size 464
		.amdhsa_user_sgpr_count 2
		.amdhsa_user_sgpr_dispatch_ptr 0
		.amdhsa_user_sgpr_queue_ptr 0
		.amdhsa_user_sgpr_kernarg_segment_ptr 1
		.amdhsa_user_sgpr_dispatch_id 0
		.amdhsa_user_sgpr_kernarg_preload_length 0
		.amdhsa_user_sgpr_kernarg_preload_offset 0
		.amdhsa_user_sgpr_private_segment_size 0
		.amdhsa_uses_dynamic_stack 0
		.amdhsa_enable_private_segment 0
		.amdhsa_system_sgpr_workgroup_id_x 1
		.amdhsa_system_sgpr_workgroup_id_y 0
		.amdhsa_system_sgpr_workgroup_id_z 0
		.amdhsa_system_sgpr_workgroup_info 0
		.amdhsa_system_vgpr_workitem_id 2
		.amdhsa_next_free_vgpr 256
		.amdhsa_next_free_sgpr 102
		.amdhsa_accum_offset 256
		.amdhsa_reserve_vcc 1
		.amdhsa_float_round_mode_32 0
		.amdhsa_float_round_mode_16_64 0
		.amdhsa_float_denorm_mode_32 3
		.amdhsa_float_denorm_mode_16_64 3
		.amdhsa_dx10_clamp 1
		.amdhsa_ieee_mode 1
		.amdhsa_fp16_overflow 0
		.amdhsa_tg_split 0
		.amdhsa_exception_fp_ieee_invalid_op 0
		.amdhsa_exception_fp_denorm_src 0
		.amdhsa_exception_fp_ieee_div_zero 0
		.amdhsa_exception_fp_ieee_overflow 0
		.amdhsa_exception_fp_ieee_underflow 0
		.amdhsa_exception_fp_ieee_inexact 0
		.amdhsa_exception_int_div_zero 0
	.end_amdhsa_kernel

amdhsa.kernels:
  - .agpr_count:     0
    .args:
      - .offset:         0
        .size:           208
        .value_kind:     by_value
      - .offset:         208
        .size:           4
        .value_kind:     hidden_block_count_x
      - .offset:         212
        .size:           4
        .value_kind:     hidden_block_count_y
      - .offset:         216
        .size:           4
        .value_kind:     hidden_block_count_z
      - .offset:         220
        .size:           2
        .value_kind:     hidden_group_size_x
      - .offset:         222
        .size:           2
        .value_kind:     hidden_group_size_y
      - .offset:         224
        .size:           2
        .value_kind:     hidden_group_size_z
      - .offset:         226
        .size:           2
        .value_kind:     hidden_remainder_x
      - .offset:         228
        .size:           2
        .value_kind:     hidden_remainder_y
      - .offset:         230
        .size:           2
        .value_kind:     hidden_remainder_z
      - .offset:         248
        .size:           8
        .value_kind:     hidden_global_offset_x
      - .offset:         256
        .size:           8
        .value_kind:     hidden_global_offset_y
      - .offset:         264
        .size:           8
        .value_kind:     hidden_global_offset_z
      - .offset:         272
        .size:           2
        .value_kind:     hidden_grid_dims
      - .offset:         296
        .size:           8
        .value_kind:     hidden_multigrid_sync_arg
      - .offset:         328
        .size:           4
        .value_kind:     hidden_dynamic_lds_size
    .group_segment_fixed_size: 0
    .kernarg_segment_align: 8
    .kernarg_segment_size: 464
    .language:       OpenCL C
    .language_version:
      - 2
      - 0
    .max_flat_workgroup_size: 512
    .name:           _Z6mk_fwd6Params
    .private_segment_fixed_size: 0
    .sgpr_count:     108
    .sgpr_spill_count: 228
    .symbol:         _Z6mk_fwd6Params.kd
    .uniform_work_group_size: 1
    .uses_dynamic_stack: false
    .vgpr_count:     256
    .vgpr_spill_count: 0
    .wavefront_size: 64
